# mini residual GEMMs: 37-40 loads in flight with counted vmcnt instead of vmcnt(0) per k-step; Y1 barrier after next-tile setup in GU
# speedup vs baseline: 1.0016x; 1.0016x over previous
.LBB0_1313:
	s_and_b32 s6, s11, 0xffffffe0
	v_or_b32_e32 v0, s6, v221
	s_and_b32 s13, s12, 15
	v_mad_i64_i32 v[12:13], s[4:5], v0, s14, 0
	v_lshlrev_b32_e32 v0, 12, v221
	v_lshl_or_b32 v0, s13, 18, v0
	v_lshl_add_u64 v[20:21], v[6:7], 0, v[0:1]
	s_mov_b32 s4, 0x10000
	v_add_co_u32_e64 v14, s[4:5], s4, v20
	v_lshl_add_u64 v[18:19], v[12:13], 1, v[4:5]
	s_nop 0
	v_addc_co_u32_e64 v15, s[4:5], 0, v21, s[4:5]
	s_mov_b32 s4, 0x20000
	s_nop 0
	v_add_co_u32_e64 v12, s[4:5], s4, v20
	v_lshl_add_u64 v[22:23], v[18:19], 0, s[92:93]
	s_nop 0
	s_nop 0
	v_addc_co_u32_e64 v13, s[4:5], 0, v21, s[4:5]
	s_nop 0
	s_mov_b32 s4, 0x30000
	v_add_co_u32_e64 v16, s[4:5], s4, v20
	s_nop 0
	s_nop 0
	v_addc_co_u32_e64 v17, s[4:5], 0, v21, s[4:5]
	s_nop 0
	s_nop 0
	s_nop 0
	s_nop 0
	s_nop 0
	s_nop 0
	v_add_u32_e32 v0, 0x1000, v28
	s_ashr_i32 s7, s6, 31
	v_readlane_b32 s4, v254, 28
	v_readlane_b32 s5, v254, 29
	v_mov_b32_e32 v11, v1
	v_mov_b32_e32 v159, v158
	global_load_dwordx4 v[62:65], v[18:19], off
	global_load_dwordx4 v[66:69], v[22:23], off
	global_load_dwordx4 v[70:73], v[20:21], off
	global_load_dwordx4 v[74:77], v[14:15], off
	global_load_dwordx4 v[78:81], v[12:13], off
	global_load_dwordx4 v[82:85], v[16:17], off
	global_load_dwordx4 v[86:89], v[18:19], off offset:64
	global_load_dwordx4 v[90:93], v[22:23], off offset:64
	global_load_dwordx4 v[94:97], v[20:21], off offset:64
	global_load_dwordx4 v[98:101], v[14:15], off offset:64
	global_load_dwordx4 v[102:105], v[12:13], off offset:64
	global_load_dwordx4 v[106:109], v[16:17], off offset:64
	global_load_dwordx4 v[110:113], v[18:19], off offset:128
	global_load_dwordx4 v[114:117], v[22:23], off offset:128
	global_load_dwordx4 v[118:121], v[20:21], off offset:128
	global_load_dwordx4 v[122:125], v[14:15], off offset:128
	global_load_dwordx4 v[126:129], v[12:13], off offset:128
	global_load_dwordx4 v[130:133], v[16:17], off offset:128
	global_load_dwordx4 v[134:137], v[18:19], off offset:192
	global_load_dwordx4 v[138:141], v[22:23], off offset:192
	global_load_dwordx4 v[142:145], v[20:21], off offset:192
	global_load_dwordx4 v[146:149], v[14:15], off offset:192
	global_load_dwordx4 v[150:153], v[12:13], off offset:192
	global_load_dwordx4 v[154:157], v[16:17], off offset:192
	global_load_dwordx4 v[160:163], v[18:19], off offset:256
	global_load_dwordx4 v[170:173], v[22:23], off offset:256
	global_load_dwordx4 v[174:177], v[20:21], off offset:256
	global_load_dwordx4 v[178:181], v[14:15], off offset:256
	global_load_dwordx4 v[182:185], v[12:13], off offset:256
	global_load_dwordx4 v[186:189], v[16:17], off offset:256
	global_load_dwordx4 v[190:193], v[18:19], off offset:320
	global_load_dwordx4 v[194:197], v[22:23], off offset:320
	global_load_dwordx4 v[198:201], v[20:21], off offset:320
	global_load_dwordx4 v[202:205], v[14:15], off offset:320
	global_load_dwordx4 v[206:209], v[12:13], off offset:320
	global_load_dwordx4 v[214:217], v[16:17], off offset:320
	global_load_dwordx4 v[224:227], v[18:19], off offset:384
	global_load_dwordx4 v[228:231], v[22:23], off offset:384
	global_load_dwordx4 v[232:235], v[20:21], off offset:384
	global_load_dwordx4 v[236:239], v[14:15], off offset:384
	s_waitcnt vmcnt(34)
	v_mfma_f32_16x16x32_bf16 v[30:33], v[62:65], v[70:73], 0
	v_mfma_f32_16x16x32_bf16 v[34:37], v[62:65], v[74:77], 0
	v_mfma_f32_16x16x32_bf16 v[38:41], v[62:65], v[78:81], 0
	v_mfma_f32_16x16x32_bf16 v[42:45], v[62:65], v[82:85], 0
	v_mfma_f32_16x16x32_bf16 v[46:49], v[66:69], v[70:73], 0
	v_mfma_f32_16x16x32_bf16 v[50:53], v[66:69], v[74:77], 0
	v_mfma_f32_16x16x32_bf16 v[54:57], v[66:69], v[78:81], 0
	v_mfma_f32_16x16x32_bf16 v[58:61], v[66:69], v[82:85], 0
	global_load_dwordx4 v[62:65], v[12:13], off offset:384
	global_load_dwordx4 v[66:69], v[16:17], off offset:384
	global_load_dwordx4 v[70:73], v[18:19], off offset:448
	global_load_dwordx4 v[74:77], v[22:23], off offset:448
	global_load_dwordx4 v[78:81], v[20:21], off offset:448
	global_load_dwordx4 v[82:85], v[14:15], off offset:448
	s_waitcnt vmcnt(34)
	v_mfma_f32_16x16x32_bf16 v[30:33], v[86:89], v[94:97], v[30:33]
	v_mfma_f32_16x16x32_bf16 v[34:37], v[86:89], v[98:101], v[34:37]
	v_mfma_f32_16x16x32_bf16 v[38:41], v[86:89], v[102:105], v[38:41]
	v_mfma_f32_16x16x32_bf16 v[42:45], v[86:89], v[106:109], v[42:45]
	v_mfma_f32_16x16x32_bf16 v[46:49], v[90:93], v[94:97], v[46:49]
	v_mfma_f32_16x16x32_bf16 v[50:53], v[90:93], v[98:101], v[50:53]
	v_mfma_f32_16x16x32_bf16 v[54:57], v[90:93], v[102:105], v[54:57]
	v_mfma_f32_16x16x32_bf16 v[58:61], v[90:93], v[106:109], v[58:61]
	global_load_dwordx4 v[86:89], v[12:13], off offset:448
	global_load_dwordx4 v[90:93], v[16:17], off offset:448
	s_waitcnt vmcnt(30)
	v_mfma_f32_16x16x32_bf16 v[30:33], v[110:113], v[118:121], v[30:33]
	v_mfma_f32_16x16x32_bf16 v[34:37], v[110:113], v[122:125], v[34:37]
	v_mfma_f32_16x16x32_bf16 v[38:41], v[110:113], v[126:129], v[38:41]
	v_mfma_f32_16x16x32_bf16 v[42:45], v[110:113], v[130:133], v[42:45]
	v_mfma_f32_16x16x32_bf16 v[46:49], v[114:117], v[118:121], v[46:49]
	v_mfma_f32_16x16x32_bf16 v[50:53], v[114:117], v[122:125], v[50:53]
	v_mfma_f32_16x16x32_bf16 v[54:57], v[114:117], v[126:129], v[54:57]
	v_mfma_f32_16x16x32_bf16 v[58:61], v[114:117], v[130:133], v[58:61]
	s_waitcnt vmcnt(24)
	v_mfma_f32_16x16x32_bf16 v[30:33], v[134:137], v[142:145], v[30:33]
	v_mfma_f32_16x16x32_bf16 v[34:37], v[134:137], v[146:149], v[34:37]
	v_mfma_f32_16x16x32_bf16 v[38:41], v[134:137], v[150:153], v[38:41]
	v_mfma_f32_16x16x32_bf16 v[42:45], v[134:137], v[154:157], v[42:45]
	v_mfma_f32_16x16x32_bf16 v[46:49], v[138:141], v[142:145], v[46:49]
	v_mfma_f32_16x16x32_bf16 v[50:53], v[138:141], v[146:149], v[50:53]
	v_mfma_f32_16x16x32_bf16 v[54:57], v[138:141], v[150:153], v[54:57]
	v_mfma_f32_16x16x32_bf16 v[58:61], v[138:141], v[154:157], v[58:61]
	s_waitcnt vmcnt(18)
	v_mfma_f32_16x16x32_bf16 v[30:33], v[160:163], v[174:177], v[30:33]
	v_mfma_f32_16x16x32_bf16 v[34:37], v[160:163], v[178:181], v[34:37]
	v_mfma_f32_16x16x32_bf16 v[38:41], v[160:163], v[182:185], v[38:41]
	v_mfma_f32_16x16x32_bf16 v[42:45], v[160:163], v[186:189], v[42:45]
	v_mfma_f32_16x16x32_bf16 v[46:49], v[170:173], v[174:177], v[46:49]
	v_mfma_f32_16x16x32_bf16 v[50:53], v[170:173], v[178:181], v[50:53]
	v_mfma_f32_16x16x32_bf16 v[54:57], v[170:173], v[182:185], v[54:57]
	v_mfma_f32_16x16x32_bf16 v[58:61], v[170:173], v[186:189], v[58:61]
	s_waitcnt vmcnt(12)
	v_mfma_f32_16x16x32_bf16 v[30:33], v[190:193], v[198:201], v[30:33]
	v_mfma_f32_16x16x32_bf16 v[34:37], v[190:193], v[202:205], v[34:37]
	v_mfma_f32_16x16x32_bf16 v[38:41], v[190:193], v[206:209], v[38:41]
	v_mfma_f32_16x16x32_bf16 v[42:45], v[190:193], v[214:217], v[42:45]
	v_mfma_f32_16x16x32_bf16 v[46:49], v[194:197], v[198:201], v[46:49]
	v_mfma_f32_16x16x32_bf16 v[50:53], v[194:197], v[202:205], v[50:53]
	v_mfma_f32_16x16x32_bf16 v[54:57], v[194:197], v[206:209], v[54:57]
	v_mfma_f32_16x16x32_bf16 v[58:61], v[194:197], v[214:217], v[58:61]
	s_waitcnt vmcnt(6)
	v_mfma_f32_16x16x32_bf16 v[30:33], v[224:227], v[232:235], v[30:33]
	v_mfma_f32_16x16x32_bf16 v[34:37], v[224:227], v[236:239], v[34:37]
	v_mfma_f32_16x16x32_bf16 v[38:41], v[224:227], v[62:65], v[38:41]
	v_mfma_f32_16x16x32_bf16 v[42:45], v[224:227], v[66:69], v[42:45]
	v_mfma_f32_16x16x32_bf16 v[46:49], v[228:231], v[232:235], v[46:49]
	v_mfma_f32_16x16x32_bf16 v[50:53], v[228:231], v[236:239], v[50:53]
	v_mfma_f32_16x16x32_bf16 v[54:57], v[228:231], v[62:65], v[54:57]
	v_mfma_f32_16x16x32_bf16 v[58:61], v[228:231], v[66:69], v[58:61]
	s_waitcnt vmcnt(0)
	v_mfma_f32_16x16x32_bf16 v[30:33], v[70:73], v[78:81], v[30:33]
	v_mfma_f32_16x16x32_bf16 v[34:37], v[70:73], v[82:85], v[34:37]
	v_mfma_f32_16x16x32_bf16 v[38:41], v[70:73], v[86:89], v[38:41]
	v_mfma_f32_16x16x32_bf16 v[42:45], v[70:73], v[90:93], v[42:45]
	v_mfma_f32_16x16x32_bf16 v[46:49], v[74:77], v[78:81], v[46:49]
	v_mfma_f32_16x16x32_bf16 v[50:53], v[74:77], v[82:85], v[50:53]
	v_mfma_f32_16x16x32_bf16 v[54:57], v[74:77], v[86:89], v[54:57]
	v_mfma_f32_16x16x32_bf16 v[58:61], v[74:77], v[90:93], v[58:61]
	s_nop 7
	s_nop 3
	ds_write2_b32 v28, v30, v34 offset0:0 offset1:16
	ds_write2_b32 v28, v31, v35 offset0:64 offset1:80
	ds_write2_b32 v28, v32, v36 offset0:128 offset1:144
	ds_write2_b32 v28, v33, v37 offset0:192 offset1:208
	ds_write2_b32 v28, v38, v42 offset0:32 offset1:48
	ds_write2_b32 v28, v39, v43 offset0:96 offset1:112
	ds_write2_b32 v28, v40, v44 offset0:160 offset1:176
	ds_write2_b32 v28, v41, v45 offset0:224 offset1:240
	ds_write2_b32 v0, v46, v50 offset0:0 offset1:16
	ds_write2_b32 v0, v47, v51 offset0:64 offset1:80
	ds_write2_b32 v0, v48, v52 offset0:128 offset1:144
	ds_write2_b32 v0, v49, v53 offset0:192 offset1:208
	ds_write2_b32 v0, v54, v58 offset0:32 offset1:48
	ds_write2_b32 v0, v55, v59 offset0:96 offset1:112
	ds_write2_b32 v0, v56, v60 offset0:160 offset1:176
	ds_write2_b32 v0, v57, v61 offset0:224 offset1:240
	v_lshl_add_u64 v[12:13], v[8:9], 0, s[6:7]
	v_lshlrev_b64 v[14:15], 11, v[12:13]
	v_lshl_add_u64 v[14:15], s[4:5], 0, v[14:15]
	s_lshl_b32 s4, s13, 7
	s_mov_b32 s5, s93
	v_lshl_add_u64 v[14:15], v[14:15], 0, s[4:5]
	v_lshl_add_u64 v[34:35], v[14:15], 0, v[10:11]
	s_waitcnt lgkmcnt(0)
	s_barrier
	global_load_dwordx2 v[36:37], v[34:35], off
	ds_read_b128 v[14:17], v29
	ds_read_b128 v[18:21], v29 offset:8192
	ds_read_b128 v[30:33], v29 offset:16384
	s_waitcnt lgkmcnt(2)
	v_pk_add_f32 v[16:17], v[16:17], 0 op_sel_hi:[1,0]
	v_pk_add_f32 v[22:23], v[14:15], 0 op_sel_hi:[1,0]
	s_waitcnt lgkmcnt(1)
	v_pk_add_f32 v[20:21], v[16:17], v[20:21]
	ds_read_b128 v[14:17], v29 offset:24576
	v_pk_add_f32 v[22:23], v[22:23], v[18:19]
	s_waitcnt lgkmcnt(1)
	v_pk_add_f32 v[32:33], v[20:21], v[32:33]
	ds_read_b128 v[18:21], v29 offset:32768
	v_pk_add_f32 v[22:23], v[22:23], v[30:31]
	s_waitcnt lgkmcnt(1)
	v_pk_add_f32 v[30:31], v[32:33], v[16:17]
	v_pk_add_f32 v[32:33], v[22:23], v[14:15]
	ds_read_b128 v[14:17], v29 offset:40960
	s_waitcnt lgkmcnt(1)
	v_pk_add_f32 v[38:39], v[30:31], v[20:21]
	ds_read_b128 v[20:23], v29 offset:49152
	v_pk_add_f32 v[18:19], v[32:33], v[18:19]
	ds_read_b128 v[30:33], v29 offset:57344
	s_waitcnt lgkmcnt(2)
	v_pk_add_f32 v[16:17], v[38:39], v[16:17]
	v_pk_add_f32 v[14:15], v[18:19], v[14:15]
	s_waitcnt lgkmcnt(1)
	v_pk_add_f32 v[16:17], v[16:17], v[22:23]
	v_pk_add_f32 v[14:15], v[14:15], v[20:21]
	s_waitcnt lgkmcnt(0)
	v_pk_add_f32 v[16:17], v[16:17], v[32:33]
	v_pk_add_f32 v[14:15], v[14:15], v[30:31]
	s_waitcnt vmcnt(0)
	v_lshlrev_b32_e32 v18, 16, v36
	v_and_b32_e32 v19, 0xffff0000, v36
	v_lshlrev_b32_e32 v20, 16, v37
	v_and_b32_e32 v21, 0xffff0000, v37
	v_pk_fma_f32 v[16:17], v[158:159], v[16:17], v[20:21]
	v_pk_fma_f32 v[14:15], v[2:3], v[14:15], v[18:19]
	v_mul_f32_e32 v11, v17, v17
	v_mul_f32_e32 v0, v15, v15
	v_fmac_f32_e32 v0, v14, v14
	v_fmac_f32_e32 v11, v16, v16
	v_add_f32_e32 v0, v0, v11
	ds_bpermute_b32 v11, v24, v0
	v_cvt_pk_bf16_f32 v14, v14, v15
	v_cvt_pk_bf16_f32 v15, v16, v17
	global_store_dwordx2 v[34:35], v[14:15], off
	s_waitcnt lgkmcnt(0)
	v_add_f32_e32 v0, v0, v11
	ds_bpermute_b32 v11, v25, v0
	s_waitcnt lgkmcnt(0)
	v_add_f32_e32 v0, v0, v11
	ds_bpermute_b32 v11, v26, v0
	s_waitcnt lgkmcnt(0)
	v_add_f32_e32 v0, v0, v11
	ds_bpermute_b32 v11, v27, v0
	s_and_saveexec_b64 s[4:5], vcc
	s_cbranch_execz .LBB0_1312
	v_readlane_b32 s6, v254, 30
	v_lshlrev_b64 v[12:13], 6, v[12:13]
	v_readlane_b32 s7, v254, 31
	s_waitcnt lgkmcnt(0)
	v_add_f32_e32 v0, v0, v11
	v_lshl_add_u64 v[12:13], s[6:7], 0, v[12:13]
	s_lshl_b32 s6, s13, 2
	s_mov_b32 s7, s93
	v_lshl_add_u64 v[12:13], v[12:13], 0, s[6:7]
	global_store_dword v[12:13], v0, off
	s_branch .LBB0_1312

.LBB0_1320:
	s_and_b32 s13, s12, 15
	s_and_b32 s6, s11, 0xffffffe0
	s_lshl_b32 s14, s13, 6
	v_or_b32_e32 v0, s6, v221
	s_movk_i32 s7, 0x1600
	v_mad_i64_i32 v[26:27], s[16:17], v0, s7, v[60:61]
	v_or_b32_e32 v0, s14, v221
	v_mul_u32_u24_e32 v0, 0x1600, v0
	v_add_co_u32_e32 v28, vcc, 0x16000, v26
	v_lshl_add_u64 v[42:43], v[62:63], 0, v[0:1]
	s_nop 0
	v_addc_co_u32_e32 v29, vcc, 0, v27, vcc
	v_add_co_u32_e32 v46, vcc, 0x16000, v42
	s_nop 0
	s_nop 0
	v_addc_co_u32_e32 v47, vcc, 0, v43, vcc
	v_add_co_u32_e32 v50, vcc, 0x2c000, v42
	s_nop 0
	s_nop 0
	v_addc_co_u32_e32 v51, vcc, 0, v43, vcc
	v_add_co_u32_e32 v54, vcc, 0x42000, v42
	s_nop 0
	s_nop 0
	v_addc_co_u32_e32 v55, vcc, 0, v43, vcc
	s_nop 0
	v_add_u32_e32 v0, 0x1000, v71
	s_ashr_i32 s7, s6, 31
	v_mov_b32_e32 v159, v158
	s_andn2_b64 vcc, exec, s[4:5]
	global_load_dwordx4 v[74:77], v[26:27], off
	global_load_dwordx4 v[78:81], v[28:29], off
	global_load_dwordx4 v[82:85], v[42:43], off
	global_load_dwordx4 v[86:89], v[46:47], off
	global_load_dwordx4 v[90:93], v[50:51], off
	global_load_dwordx4 v[94:97], v[54:55], off
	global_load_dwordx4 v[98:101], v[26:27], off offset:64
	global_load_dwordx4 v[102:105], v[28:29], off offset:64
	global_load_dwordx4 v[106:109], v[42:43], off offset:64
	global_load_dwordx4 v[110:113], v[46:47], off offset:64
	global_load_dwordx4 v[114:117], v[50:51], off offset:64
	global_load_dwordx4 v[118:121], v[54:55], off offset:64
	global_load_dwordx4 v[122:125], v[26:27], off offset:128
	global_load_dwordx4 v[126:129], v[28:29], off offset:128
	global_load_dwordx4 v[130:133], v[42:43], off offset:128
	global_load_dwordx4 v[134:137], v[46:47], off offset:128
	global_load_dwordx4 v[138:141], v[50:51], off offset:128
	global_load_dwordx4 v[142:145], v[54:55], off offset:128
	global_load_dwordx4 v[146:149], v[26:27], off offset:192
	global_load_dwordx4 v[150:153], v[28:29], off offset:192
	global_load_dwordx4 v[154:157], v[42:43], off offset:192
	global_load_dwordx4 v[160:163], v[46:47], off offset:192
	global_load_dwordx4 v[170:173], v[50:51], off offset:192
	global_load_dwordx4 v[174:177], v[54:55], off offset:192
	global_load_dwordx4 v[178:181], v[26:27], off offset:256
	global_load_dwordx4 v[182:185], v[28:29], off offset:256
	global_load_dwordx4 v[186:189], v[42:43], off offset:256
	global_load_dwordx4 v[190:193], v[46:47], off offset:256
	global_load_dwordx4 v[194:197], v[50:51], off offset:256
	global_load_dwordx4 v[198:201], v[54:55], off offset:256
	global_load_dwordx4 v[202:205], v[26:27], off offset:320
	global_load_dwordx4 v[206:209], v[28:29], off offset:320
	global_load_dwordx4 v[214:217], v[42:43], off offset:320
	global_load_dwordx4 v[224:227], v[46:47], off offset:320
	global_load_dwordx4 v[228:231], v[50:51], off offset:320
	global_load_dwordx4 v[232:235], v[54:55], off offset:320
	global_load_dwordx4 v[236:239], v[26:27], off offset:384
	s_waitcnt vmcnt(31)
	v_mfma_f32_16x16x32_bf16 v[2:5], v[74:77], v[82:85], 0
	v_mfma_f32_16x16x32_bf16 v[6:9], v[74:77], v[86:89], 0
	v_mfma_f32_16x16x32_bf16 v[10:13], v[74:77], v[90:93], 0
	v_mfma_f32_16x16x32_bf16 v[14:17], v[74:77], v[94:97], 0
	v_mfma_f32_16x16x32_bf16 v[18:21], v[78:81], v[82:85], 0
	v_mfma_f32_16x16x32_bf16 v[22:25], v[78:81], v[86:89], 0
	v_mfma_f32_16x16x32_bf16 v[30:33], v[78:81], v[90:93], 0
	v_mfma_f32_16x16x32_bf16 v[34:37], v[78:81], v[94:97], 0
	global_load_dwordx4 v[74:77], v[28:29], off offset:384
	global_load_dwordx4 v[78:81], v[42:43], off offset:384
	global_load_dwordx4 v[82:85], v[46:47], off offset:384
	global_load_dwordx4 v[86:89], v[50:51], off offset:384
	global_load_dwordx4 v[90:93], v[54:55], off offset:384
	global_load_dwordx4 v[94:97], v[26:27], off offset:448
	s_waitcnt vmcnt(31)
	v_mfma_f32_16x16x32_bf16 v[2:5], v[98:101], v[106:109], v[2:5]
	v_mfma_f32_16x16x32_bf16 v[6:9], v[98:101], v[110:113], v[6:9]
	v_mfma_f32_16x16x32_bf16 v[10:13], v[98:101], v[114:117], v[10:13]
	v_mfma_f32_16x16x32_bf16 v[14:17], v[98:101], v[118:121], v[14:17]
	v_mfma_f32_16x16x32_bf16 v[18:21], v[102:105], v[106:109], v[18:21]
	v_mfma_f32_16x16x32_bf16 v[22:25], v[102:105], v[110:113], v[22:25]
	v_mfma_f32_16x16x32_bf16 v[30:33], v[102:105], v[114:117], v[30:33]
	v_mfma_f32_16x16x32_bf16 v[34:37], v[102:105], v[118:121], v[34:37]
	global_load_dwordx4 v[98:101], v[28:29], off offset:448
	global_load_dwordx4 v[102:105], v[42:43], off offset:448
	global_load_dwordx4 v[106:109], v[46:47], off offset:448
	global_load_dwordx4 v[110:113], v[50:51], off offset:448
	global_load_dwordx4 v[114:117], v[54:55], off offset:448
	global_load_dwordx4 v[118:121], v[26:27], off offset:512
	s_waitcnt vmcnt(31)
	v_mfma_f32_16x16x32_bf16 v[2:5], v[122:125], v[130:133], v[2:5]
	v_mfma_f32_16x16x32_bf16 v[6:9], v[122:125], v[134:137], v[6:9]
	v_mfma_f32_16x16x32_bf16 v[10:13], v[122:125], v[138:141], v[10:13]
	v_mfma_f32_16x16x32_bf16 v[14:17], v[122:125], v[142:145], v[14:17]
	v_mfma_f32_16x16x32_bf16 v[18:21], v[126:129], v[130:133], v[18:21]
	v_mfma_f32_16x16x32_bf16 v[22:25], v[126:129], v[134:137], v[22:25]
	v_mfma_f32_16x16x32_bf16 v[30:33], v[126:129], v[138:141], v[30:33]
	v_mfma_f32_16x16x32_bf16 v[34:37], v[126:129], v[142:145], v[34:37]
	global_load_dwordx4 v[122:125], v[28:29], off offset:512
	global_load_dwordx4 v[126:129], v[42:43], off offset:512
	global_load_dwordx4 v[130:133], v[46:47], off offset:512
	global_load_dwordx4 v[134:137], v[50:51], off offset:512
	global_load_dwordx4 v[138:141], v[54:55], off offset:512
	global_load_dwordx4 v[142:145], v[26:27], off offset:576
	s_waitcnt vmcnt(31)
	v_mfma_f32_16x16x32_bf16 v[2:5], v[146:149], v[154:157], v[2:5]
	v_mfma_f32_16x16x32_bf16 v[6:9], v[146:149], v[160:163], v[6:9]
	v_mfma_f32_16x16x32_bf16 v[10:13], v[146:149], v[170:173], v[10:13]
	v_mfma_f32_16x16x32_bf16 v[14:17], v[146:149], v[174:177], v[14:17]
	v_mfma_f32_16x16x32_bf16 v[18:21], v[150:153], v[154:157], v[18:21]
	v_mfma_f32_16x16x32_bf16 v[22:25], v[150:153], v[160:163], v[22:25]
	v_mfma_f32_16x16x32_bf16 v[30:33], v[150:153], v[170:173], v[30:33]
	v_mfma_f32_16x16x32_bf16 v[34:37], v[150:153], v[174:177], v[34:37]
	global_load_dwordx4 v[146:149], v[28:29], off offset:576
	global_load_dwordx4 v[150:153], v[42:43], off offset:576
	global_load_dwordx4 v[154:157], v[46:47], off offset:576
	global_load_dwordx4 v[160:163], v[50:51], off offset:576
	global_load_dwordx4 v[170:173], v[54:55], off offset:576
	global_load_dwordx4 v[174:177], v[26:27], off offset:640
	s_waitcnt vmcnt(31)
	v_mfma_f32_16x16x32_bf16 v[2:5], v[178:181], v[186:189], v[2:5]
	v_mfma_f32_16x16x32_bf16 v[6:9], v[178:181], v[190:193], v[6:9]
	v_mfma_f32_16x16x32_bf16 v[10:13], v[178:181], v[194:197], v[10:13]
	v_mfma_f32_16x16x32_bf16 v[14:17], v[178:181], v[198:201], v[14:17]
	v_mfma_f32_16x16x32_bf16 v[18:21], v[182:185], v[186:189], v[18:21]
	v_mfma_f32_16x16x32_bf16 v[22:25], v[182:185], v[190:193], v[22:25]
	v_mfma_f32_16x16x32_bf16 v[30:33], v[182:185], v[194:197], v[30:33]
	v_mfma_f32_16x16x32_bf16 v[34:37], v[182:185], v[198:201], v[34:37]
	global_load_dwordx4 v[178:181], v[28:29], off offset:640
	global_load_dwordx4 v[182:185], v[42:43], off offset:640
	global_load_dwordx4 v[186:189], v[46:47], off offset:640
	global_load_dwordx4 v[190:193], v[50:51], off offset:640
	global_load_dwordx4 v[194:197], v[54:55], off offset:640
	s_waitcnt vmcnt(30)
	v_mfma_f32_16x16x32_bf16 v[2:5], v[202:205], v[214:217], v[2:5]
	v_mfma_f32_16x16x32_bf16 v[6:9], v[202:205], v[224:227], v[6:9]
	v_mfma_f32_16x16x32_bf16 v[10:13], v[202:205], v[228:231], v[10:13]
	v_mfma_f32_16x16x32_bf16 v[14:17], v[202:205], v[232:235], v[14:17]
	v_mfma_f32_16x16x32_bf16 v[18:21], v[206:209], v[214:217], v[18:21]
	v_mfma_f32_16x16x32_bf16 v[22:25], v[206:209], v[224:227], v[22:25]
	v_mfma_f32_16x16x32_bf16 v[30:33], v[206:209], v[228:231], v[30:33]
	v_mfma_f32_16x16x32_bf16 v[34:37], v[206:209], v[232:235], v[34:37]
	s_waitcnt vmcnt(24)
	v_mfma_f32_16x16x32_bf16 v[2:5], v[236:239], v[78:81], v[2:5]
	v_mfma_f32_16x16x32_bf16 v[6:9], v[236:239], v[82:85], v[6:9]
	v_mfma_f32_16x16x32_bf16 v[10:13], v[236:239], v[86:89], v[10:13]
	v_mfma_f32_16x16x32_bf16 v[14:17], v[236:239], v[90:93], v[14:17]
	v_mfma_f32_16x16x32_bf16 v[18:21], v[74:77], v[78:81], v[18:21]
	v_mfma_f32_16x16x32_bf16 v[22:25], v[74:77], v[82:85], v[22:25]
	v_mfma_f32_16x16x32_bf16 v[30:33], v[74:77], v[86:89], v[30:33]
	v_mfma_f32_16x16x32_bf16 v[34:37], v[74:77], v[90:93], v[34:37]
	s_waitcnt vmcnt(18)
	v_mfma_f32_16x16x32_bf16 v[2:5], v[94:97], v[102:105], v[2:5]
	v_mfma_f32_16x16x32_bf16 v[6:9], v[94:97], v[106:109], v[6:9]
	v_mfma_f32_16x16x32_bf16 v[10:13], v[94:97], v[110:113], v[10:13]
	v_mfma_f32_16x16x32_bf16 v[14:17], v[94:97], v[114:117], v[14:17]
	v_mfma_f32_16x16x32_bf16 v[18:21], v[98:101], v[102:105], v[18:21]
	v_mfma_f32_16x16x32_bf16 v[22:25], v[98:101], v[106:109], v[22:25]
	v_mfma_f32_16x16x32_bf16 v[30:33], v[98:101], v[110:113], v[30:33]
	v_mfma_f32_16x16x32_bf16 v[34:37], v[98:101], v[114:117], v[34:37]
	s_waitcnt vmcnt(12)
	v_mfma_f32_16x16x32_bf16 v[2:5], v[118:121], v[126:129], v[2:5]
	v_mfma_f32_16x16x32_bf16 v[6:9], v[118:121], v[130:133], v[6:9]
	v_mfma_f32_16x16x32_bf16 v[10:13], v[118:121], v[134:137], v[10:13]
	v_mfma_f32_16x16x32_bf16 v[14:17], v[118:121], v[138:141], v[14:17]
	v_mfma_f32_16x16x32_bf16 v[18:21], v[122:125], v[126:129], v[18:21]
	v_mfma_f32_16x16x32_bf16 v[22:25], v[122:125], v[130:133], v[22:25]
	v_mfma_f32_16x16x32_bf16 v[30:33], v[122:125], v[134:137], v[30:33]
	v_mfma_f32_16x16x32_bf16 v[34:37], v[122:125], v[138:141], v[34:37]
	s_waitcnt vmcnt(6)
	v_mfma_f32_16x16x32_bf16 v[2:5], v[142:145], v[150:153], v[2:5]
	v_mfma_f32_16x16x32_bf16 v[6:9], v[142:145], v[154:157], v[6:9]
	v_mfma_f32_16x16x32_bf16 v[10:13], v[142:145], v[160:163], v[10:13]
	v_mfma_f32_16x16x32_bf16 v[14:17], v[142:145], v[170:173], v[14:17]
	v_mfma_f32_16x16x32_bf16 v[18:21], v[146:149], v[150:153], v[18:21]
	v_mfma_f32_16x16x32_bf16 v[22:25], v[146:149], v[154:157], v[22:25]
	v_mfma_f32_16x16x32_bf16 v[30:33], v[146:149], v[160:163], v[30:33]
	v_mfma_f32_16x16x32_bf16 v[34:37], v[146:149], v[170:173], v[34:37]
	s_waitcnt vmcnt(0)
	v_mfma_f32_16x16x32_bf16 v[2:5], v[174:177], v[182:185], v[2:5]
	v_mfma_f32_16x16x32_bf16 v[6:9], v[174:177], v[186:189], v[6:9]
	v_mfma_f32_16x16x32_bf16 v[10:13], v[174:177], v[190:193], v[10:13]
	v_mfma_f32_16x16x32_bf16 v[14:17], v[174:177], v[194:197], v[14:17]
	v_mfma_f32_16x16x32_bf16 v[18:21], v[178:181], v[182:185], v[18:21]
	v_mfma_f32_16x16x32_bf16 v[22:25], v[178:181], v[186:189], v[22:25]
	v_mfma_f32_16x16x32_bf16 v[30:33], v[178:181], v[190:193], v[30:33]
	v_mfma_f32_16x16x32_bf16 v[34:37], v[178:181], v[194:197], v[34:37]
	s_nop 7
	s_nop 3
	ds_write2_b32 v71, v2, v6 offset0:0 offset1:16
	ds_write2_b32 v71, v3, v7 offset0:64 offset1:80
	ds_write2_b32 v71, v4, v8 offset0:128 offset1:144
	ds_write2_b32 v71, v5, v9 offset0:192 offset1:208
	ds_write2_b32 v71, v10, v14 offset0:32 offset1:48
	ds_write2_b32 v71, v11, v15 offset0:96 offset1:112
	ds_write2_b32 v71, v12, v16 offset0:160 offset1:176
	ds_write2_b32 v71, v13, v17 offset0:224 offset1:240
	ds_write2_b32 v0, v18, v22 offset0:0 offset1:16
	ds_write2_b32 v0, v19, v23 offset0:64 offset1:80
	ds_write2_b32 v0, v20, v24 offset0:128 offset1:144
	ds_write2_b32 v0, v21, v25 offset0:192 offset1:208
	ds_write2_b32 v0, v30, v34 offset0:32 offset1:48
	ds_write2_b32 v0, v31, v35 offset0:96 offset1:112
	ds_write2_b32 v0, v32, v36 offset0:160 offset1:176
	ds_write2_b32 v0, v33, v37 offset0:224 offset1:240
	s_waitcnt lgkmcnt(0)
	s_barrier
	ds_read_b128 v[2:5], v72
	s_waitcnt lgkmcnt(0)
	v_pk_add_f32 v[6:7], v[4:5], 0 op_sel_hi:[1,0]
	v_pk_add_f32 v[8:9], v[2:3], 0 op_sel_hi:[1,0]
	ds_read_b128 v[2:5], v72 offset:8192
	s_waitcnt lgkmcnt(0)
	v_pk_add_f32 v[6:7], v[6:7], v[4:5]
	v_pk_add_f32 v[8:9], v[8:9], v[2:3]
	ds_read_b128 v[2:5], v72 offset:16384
	s_waitcnt lgkmcnt(0)
	v_pk_add_f32 v[6:7], v[6:7], v[4:5]
	v_pk_add_f32 v[8:9], v[8:9], v[2:3]
	ds_read_b128 v[2:5], v72 offset:24576
	s_waitcnt lgkmcnt(0)
	v_pk_add_f32 v[6:7], v[6:7], v[4:5]
	v_pk_add_f32 v[8:9], v[8:9], v[2:3]
	ds_read_b128 v[2:5], v72 offset:32768
	s_waitcnt lgkmcnt(0)
	v_pk_add_f32 v[6:7], v[6:7], v[4:5]
	v_pk_add_f32 v[8:9], v[8:9], v[2:3]
	ds_read_b128 v[2:5], v72 offset:40960
	s_waitcnt lgkmcnt(0)
	v_pk_add_f32 v[6:7], v[6:7], v[4:5]
	v_pk_add_f32 v[8:9], v[8:9], v[2:3]
	ds_read_b128 v[2:5], v72 offset:49152
	s_waitcnt lgkmcnt(0)
	v_pk_add_f32 v[6:7], v[6:7], v[4:5]
	v_pk_add_f32 v[8:9], v[8:9], v[2:3]
	ds_read_b128 v[2:5], v72 offset:57344
	s_waitcnt lgkmcnt(0)
	v_pk_add_f32 v[4:5], v[6:7], v[4:5]
	v_lshl_add_u64 v[6:7], v[66:67], 0, s[6:7]
	v_lshlrev_b64 v[10:11], 10, v[6:7]
	v_or_b32_e32 v0, s14, v10
	v_readlane_b32 s6, v254, 28
	v_or_b32_e32 v10, v0, v64
	v_readlane_b32 s7, v254, 29
	v_pk_add_f32 v[2:3], v[8:9], v[2:3]
	s_nop 0
	v_lshl_add_u64 v[8:9], v[10:11], 1, s[6:7]
	global_load_dwordx2 v[12:13], v[8:9], off
	s_waitcnt vmcnt(0)
	v_lshlrev_b32_e32 v14, 16, v12
	v_and_b32_e32 v15, 0xffff0000, v12
	v_lshlrev_b32_e32 v12, 16, v13
	v_and_b32_e32 v13, 0xffff0000, v13
	v_pk_fma_f32 v[2:3], v[58:59], v[2:3], v[14:15]
	v_pk_fma_f32 v[4:5], v[158:159], v[4:5], v[12:13]
	s_cbranch_vccnz .LBB0_1325
	v_readlane_b32 s6, v254, 8
	v_readlane_b32 s7, v254, 9
	s_nop 1
	v_lshl_add_u64 v[10:11], v[10:11], 2, s[6:7]
	global_store_dwordx4 v[10:11], v[2:5], off
	s_cbranch_execnz .LBB0_1323

.LBB0_1445:
	s_ashr_i32 s11, s10, 31
	s_lshl_b64 s[12:13], s[10:11], 19
	v_readlane_b32 s14, v254, 28
	v_readlane_b32 s15, v254, 29
	s_add_u32 s12, s14, s12
	s_addc_u32 s13, s15, s13
	s_and_b64 s[14:15], s[0:1], exec
	s_cselect_b32 s11, s13, s5
	s_cselect_b32 s37, s12, s4
	s_ashr_i32 s9, s8, 31
	s_lshl_b64 s[14:15], s[8:9], 19
	s_add_u32 s14, s20, s14
	s_addc_u32 s15, s21, s15
	s_and_b64 s[18:19], s[0:1], exec
	s_cselect_b32 s9, s15, s17
	s_cselect_b32 s38, s14, s16
	s_add_u32 s4, s4, 0x40080
	s_addc_u32 s5, s5, 0
	s_add_u32 s39, s16, 0x100
	s_addc_u32 s40, s17, 0
	s_mov_b32 s41, -2
	s_cmp_eq_u32 s34, 1
	s_cbranch_scc1 .Lgu_noy1
	s_andn2_b64 vcc, exec, s[2:3]
	s_cbranch_vccnz .Lgu_noy1
	s_barrier
.Lgu_noy1:
	s_add_u32 s16, s4, 0xfffc0080
	s_addc_u32 s17, s5, -1
	s_add_i32 s42, 0, 0x10000
	s_cmp_eq_u32 s41, 12
	s_cselect_b32 s19, s11, s17
	s_cselect_b32 s18, s37, s16
	s_cselect_b32 s17, s9, s40
	s_cselect_b32 s16, s38, s39
	s_add_i32 s44, 0, 0x14000
	v_add_u32_e32 v142, s42, v195
	v_add_u32_e32 v162, s44, v195
	ds_read_b128 v[130:133], v142
	ds_read_b128 v[134:137], v142 offset:1024
	ds_read_b128 v[138:141], v142 offset:2048
	ds_read_b128 v[142:145], v142 offset:3072
	ds_read_b128 v[146:149], v162
	ds_read_b128 v[150:153], v162 offset:1024
	ds_read_b128 v[174:177], v162 offset:2048
	ds_read_b128 v[178:181], v162 offset:3072
	v_lshl_add_u64 v[162:163], s[4:5], 0, v[170:171]
	s_add_i32 m0, s23, 0xc000
	ds_read_b128 v[182:185], v199
	ds_read_b128 v[186:189], v199 offset:1024
	ds_read_b128 v[200:203], v199 offset:2048
	ds_read_b128 v[204:207], v199 offset:3072
	ds_read_b128 v[220:223], v199 offset:4096
	ds_read_b128 v[224:227], v199 offset:5120
	ds_read_b128 v[228:231], v199 offset:6144
	ds_read_b128 v[232:235], v199 offset:7168
	global_load_lds_dwordx4 v[162:163], off
	v_lshl_add_u64 v[162:163], s[4:5], 0, v[172:173]
	s_add_i32 m0, s23, 0xe000
	s_nop 0
	global_load_lds_dwordx4 v[162:163], off
	s_waitcnt vmcnt(16)
	s_waitcnt lgkmcnt(0)
	s_barrier
	s_setprio 1
	s_waitcnt lgkmcnt(0)
	v_mfma_f32_16x16x32_bf16 v[126:129], v[130:133], v[182:185], 0
	v_mfma_f32_16x16x32_bf16 v[118:121], v[138:141], v[182:185], 0
	v_mfma_f32_16x16x32_bf16 v[110:113], v[130:133], v[200:203], 0
	v_mfma_f32_16x16x32_bf16 v[102:105], v[138:141], v[200:203], 0
	v_mfma_f32_16x16x32_bf16 v[94:97], v[130:133], v[220:223], 0
	v_mfma_f32_16x16x32_bf16 v[86:89], v[138:141], v[220:223], 0
	v_mfma_f32_16x16x32_bf16 v[78:81], v[130:133], v[228:231], 0
	v_mfma_f32_16x16x32_bf16 v[70:73], v[138:141], v[228:231], 0
	v_mfma_f32_16x16x32_bf16 v[126:129], v[134:137], v[186:189], v[126:129]
	v_mfma_f32_16x16x32_bf16 v[118:121], v[142:145], v[186:189], v[118:121]
	v_mfma_f32_16x16x32_bf16 v[110:113], v[134:137], v[204:207], v[110:113]
	v_mfma_f32_16x16x32_bf16 v[102:105], v[142:145], v[204:207], v[102:105]
	v_mfma_f32_16x16x32_bf16 v[94:97], v[134:137], v[224:227], v[94:97]
	v_mfma_f32_16x16x32_bf16 v[86:89], v[142:145], v[224:227], v[86:89]
	v_mfma_f32_16x16x32_bf16 v[78:81], v[134:137], v[232:235], v[78:81]
	v_mfma_f32_16x16x32_bf16 v[70:73], v[142:145], v[232:235], v[70:73]
	s_setprio 0
	s_setprio 1
	v_mfma_f32_16x16x32_bf16 v[122:125], v[146:149], v[182:185], 0
	v_mfma_f32_16x16x32_bf16 v[114:117], v[174:177], v[182:185], 0
	v_mfma_f32_16x16x32_bf16 v[106:109], v[146:149], v[200:203], 0
	v_mfma_f32_16x16x32_bf16 v[98:101], v[174:177], v[200:203], 0
	v_mfma_f32_16x16x32_bf16 v[90:93], v[146:149], v[220:223], 0
	v_mfma_f32_16x16x32_bf16 v[82:85], v[174:177], v[220:223], 0
	v_mfma_f32_16x16x32_bf16 v[74:77], v[146:149], v[228:231], 0
	v_mfma_f32_16x16x32_bf16 v[66:69], v[174:177], v[228:231], 0
	v_mfma_f32_16x16x32_bf16 v[122:125], v[150:153], v[186:189], v[122:125]
	v_mfma_f32_16x16x32_bf16 v[114:117], v[178:181], v[186:189], v[114:117]
	v_mfma_f32_16x16x32_bf16 v[106:109], v[150:153], v[204:207], v[106:109]
	v_mfma_f32_16x16x32_bf16 v[98:101], v[178:181], v[204:207], v[98:101]
	v_mfma_f32_16x16x32_bf16 v[90:93], v[150:153], v[224:227], v[90:93]
	v_mfma_f32_16x16x32_bf16 v[82:85], v[178:181], v[224:227], v[82:85]
	v_mfma_f32_16x16x32_bf16 v[74:77], v[150:153], v[232:235], v[74:77]
	v_mfma_f32_16x16x32_bf16 v[66:69], v[178:181], v[232:235], v[66:69]
	s_setprio 0
	s_barrier
	s_add_i32 s42, s42, s22
	v_lshl_add_u64 v[162:163], s[16:17], 0, v[0:1]
	s_mov_b32 m0, s42
	ds_read_b128 v[182:185], v199 offset:16384
	ds_read_b128 v[186:189], v199 offset:17408
	ds_read_b128 v[200:203], v199 offset:18432
	ds_read_b128 v[204:207], v199 offset:19456
	ds_read_b128 v[220:223], v199 offset:20480
	ds_read_b128 v[224:227], v199 offset:21504
	ds_read_b128 v[228:231], v199 offset:22528
	ds_read_b128 v[232:235], v199 offset:23552
	global_load_lds_dwordx4 v[162:163], off
	s_add_i32 m0, s42, 0x2000
	s_add_u32 s42, s16, 0x40000
	v_lshl_add_u64 v[190:191], s[16:17], 0, v[154:155]
	s_addc_u32 s43, s17, 0
	s_add_i32 s44, s44, s22
	global_load_lds_dwordx4 v[190:191], off
	v_lshl_add_u64 v[196:197], s[42:43], 0, v[0:1]
	s_mov_b32 m0, s44
	v_lshl_add_u64 v[208:209], s[18:19], 0, v[156:157]
	global_load_lds_dwordx4 v[196:197], off
	v_lshl_add_u64 v[196:197], s[42:43], 0, v[154:155]
	s_add_i32 m0, s44, 0x2000
	s_nop 0
	global_load_lds_dwordx4 v[196:197], off
	v_lshl_add_u64 v[196:197], s[18:19], 0, v[158:159]
	s_mov_b32 m0, s23
	s_nop 0
	global_load_lds_dwordx4 v[196:197], off
	s_mov_b32 m0, s26
	s_nop 0
	global_load_lds_dwordx4 v[208:209], off
	s_cmp_eq_u32 s34, 1
	s_cbranch_scc1 .Lgu_peel_w8
	s_waitcnt vmcnt(16)
	s_branch .Lgu_peel_wj

.Lgu_rs_done:
	v_readlane_b32 s4, v254, 32
	v_readlane_b32 s5, v254, 33
	v_pk_mul_f32 v[126:127], v[126:127], v[194:195] op_sel_hi:[1,0]
	v_pk_mul_f32 v[122:123], v[122:123], v[194:195] op_sel_hi:[1,0]
	v_pk_mul_f32 v[124:125], v[124:125], v[194:195] op_sel_hi:[1,0]
	v_pk_mul_f32 v[118:119], v[118:119], v[194:195] op_sel_hi:[1,0]
	v_pk_mul_f32 v[114:115], v[114:115], v[194:195] op_sel_hi:[1,0]
	v_pk_mul_f32 v[116:117], v[116:117], v[194:195] op_sel_hi:[1,0]
	v_mul_f32_e32 v131, 0xbfb8aa3b, v126
	v_exp_f32_e32 v131, v131
	v_pk_mul_f32 v[110:111], v[110:111], v[192:193] op_sel_hi:[1,0]
	v_pk_mul_f32 v[106:107], v[106:107], v[192:193] op_sel_hi:[1,0]
	v_pk_mul_f32 v[108:109], v[108:109], v[192:193] op_sel_hi:[1,0]
	v_add_f32_e32 v131, 1.0, v131
	v_rcp_f32_e32 v134, v131
	v_mul_f32_e32 v131, 0xbfb8aa3b, v127
	v_exp_f32_e32 v131, v131
	v_pk_mul_f32 v[102:103], v[102:103], v[192:193] op_sel_hi:[1,0]
	v_pk_mul_f32 v[98:99], v[98:99], v[192:193] op_sel_hi:[1,0]
	v_pk_mul_f32 v[100:101], v[100:101], v[192:193] op_sel_hi:[1,0]
	v_add_f32_e32 v131, 1.0, v131
	v_rcp_f32_e32 v135, v131
	v_pk_mul_f32 v[94:95], v[94:95], v[148:149] op_sel_hi:[1,0]
	v_pk_mul_f32 v[90:91], v[90:91], v[148:149] op_sel_hi:[1,0]
	v_pk_mul_f32 v[92:93], v[92:93], v[148:149] op_sel_hi:[1,0]
	v_pk_mul_f32 v[126:127], v[126:127], v[134:135]
	v_pk_mul_f32 v[86:87], v[86:87], v[148:149] op_sel_hi:[1,0]
	v_pk_mul_f32 v[122:123], v[122:123], v[126:127]
	v_pk_mul_f32 v[126:127], v[128:129], v[194:195] op_sel_hi:[1,0]
	v_pk_mul_f32 v[82:83], v[82:83], v[148:149] op_sel_hi:[1,0]
	v_mul_f32_e32 v128, 0xbfb8aa3b, v126
	v_mul_f32_e32 v129, 0xbfb8aa3b, v127
	v_exp_f32_e32 v128, v128
	v_exp_f32_e32 v129, v129
	v_pk_mul_f32 v[84:85], v[84:85], v[148:149] op_sel_hi:[1,0]
	v_pk_mul_f32 v[78:79], v[78:79], v[146:147] op_sel_hi:[1,0]
	v_add_f32_e32 v128, 1.0, v128
	v_add_f32_e32 v129, 1.0, v129
	v_rcp_f32_e32 v128, v128
	v_rcp_f32_e32 v129, v129
	v_pk_mul_f32 v[74:75], v[74:75], v[146:147] op_sel_hi:[1,0]
	v_pk_mul_f32 v[76:77], v[76:77], v[146:147] op_sel_hi:[1,0]
	v_pk_mul_f32 v[70:71], v[70:71], v[146:147] op_sel_hi:[1,0]
	v_pk_mul_f32 v[126:127], v[126:127], v[128:129]
	v_pk_mul_f32 v[66:67], v[66:67], v[146:147] op_sel_hi:[1,0]
	v_pk_mul_f32 v[124:125], v[124:125], v[126:127]
	v_mul_f32_e32 v126, 0xbfb8aa3b, v118
	v_mul_f32_e32 v127, 0xbfb8aa3b, v119
	v_exp_f32_e32 v126, v126
	v_exp_f32_e32 v127, v127
	v_pk_mul_f32 v[68:69], v[68:69], v[146:147] op_sel_hi:[1,0]
	v_pk_mul_f32 v[62:63], v[62:63], v[140:141] op_sel_hi:[1,0]
	v_add_f32_e32 v126, 1.0, v126
	v_add_f32_e32 v127, 1.0, v127
	v_rcp_f32_e32 v126, v126
	v_rcp_f32_e32 v127, v127
	v_pk_mul_f32 v[58:59], v[58:59], v[140:141] op_sel_hi:[1,0]
	v_pk_mul_f32 v[60:61], v[60:61], v[140:141] op_sel_hi:[1,0]
	v_pk_mul_f32 v[54:55], v[54:55], v[140:141] op_sel_hi:[1,0]
	v_pk_mul_f32 v[118:119], v[118:119], v[126:127]
	v_pk_mul_f32 v[50:51], v[50:51], v[140:141] op_sel_hi:[1,0]
	v_pk_mul_f32 v[114:115], v[114:115], v[118:119]
	v_pk_mul_f32 v[118:119], v[120:121], v[194:195] op_sel_hi:[1,0]
	v_pk_mul_f32 v[52:53], v[52:53], v[140:141] op_sel_hi:[1,0]
	v_mul_f32_e32 v120, 0xbfb8aa3b, v118
	v_mul_f32_e32 v121, 0xbfb8aa3b, v119
	v_exp_f32_e32 v120, v120
	v_exp_f32_e32 v121, v121
	v_pk_mul_f32 v[46:47], v[46:47], v[138:139] op_sel_hi:[1,0]
	v_pk_mul_f32 v[42:43], v[42:43], v[138:139] op_sel_hi:[1,0]
	v_add_f32_e32 v120, 1.0, v120
	v_add_f32_e32 v121, 1.0, v121
	v_rcp_f32_e32 v120, v120
	v_rcp_f32_e32 v121, v121
	v_pk_mul_f32 v[44:45], v[44:45], v[138:139] op_sel_hi:[1,0]
	v_pk_mul_f32 v[38:39], v[38:39], v[138:139] op_sel_hi:[1,0]
	v_pk_mul_f32 v[34:35], v[34:35], v[138:139] op_sel_hi:[1,0]
	v_pk_mul_f32 v[118:119], v[118:119], v[120:121]
	v_cvt_pk_bf16_f32 v120, v114, v115
	v_pk_mul_f32 v[116:117], v[116:117], v[118:119]
	v_mov_b64_e32 v[114:115], s[4:5]
	v_cvt_pk_bf16_f32 v118, v122, v123
	v_cvt_pk_bf16_f32 v121, v116, v117
	v_mad_i64_i32 v[122:123], s[4:5], v188, s9, v[114:115]
	v_lshlrev_b64 v[116:117], 1, v[190:191]
	v_cvt_pk_bf16_f32 v119, v124, v125
	v_lshl_add_u64 v[122:123], v[122:123], 0, v[116:117]
	global_store_dwordx4 v[122:123], v[118:121], off
	v_pk_mul_f32 v[36:37], v[36:37], v[138:139] op_sel_hi:[1,0]
	v_pk_mul_f32 v[30:31], v[30:31], v[132:133] op_sel_hi:[1,0]
	v_mul_f32_e32 v118, 0xbfb8aa3b, v110
	v_mul_f32_e32 v119, 0xbfb8aa3b, v111
	v_exp_f32_e32 v118, v118
	v_exp_f32_e32 v119, v119
	v_pk_mul_f32 v[26:27], v[26:27], v[132:133] op_sel_hi:[1,0]
	v_pk_mul_f32 v[28:29], v[28:29], v[132:133] op_sel_hi:[1,0]
	v_add_f32_e32 v118, 1.0, v118
	v_add_f32_e32 v119, 1.0, v119
	v_rcp_f32_e32 v118, v118
	v_rcp_f32_e32 v119, v119
	v_pk_mul_f32 v[22:23], v[22:23], v[132:133] op_sel_hi:[1,0]
	v_pk_mul_f32 v[18:19], v[18:19], v[132:133] op_sel_hi:[1,0]
	v_pk_mul_f32 v[20:21], v[20:21], v[132:133] op_sel_hi:[1,0]
	v_pk_mul_f32 v[110:111], v[110:111], v[118:119]
	v_pk_mul_f32 v[14:15], v[14:15], v[130:131] op_sel_hi:[1,0]
	v_pk_mul_f32 v[106:107], v[106:107], v[110:111]
	v_pk_mul_f32 v[110:111], v[112:113], v[192:193] op_sel_hi:[1,0]
	v_pk_mul_f32 v[10:11], v[10:11], v[130:131] op_sel_hi:[1,0]
	v_mul_f32_e32 v112, 0xbfb8aa3b, v110
	v_mul_f32_e32 v113, 0xbfb8aa3b, v111
	v_exp_f32_e32 v112, v112
	v_exp_f32_e32 v113, v113
	v_pk_mul_f32 v[12:13], v[12:13], v[130:131] op_sel_hi:[1,0]
	v_pk_mul_f32 v[6:7], v[6:7], v[130:131] op_sel_hi:[1,0]
	v_add_f32_e32 v112, 1.0, v112
	v_add_f32_e32 v113, 1.0, v113
	v_rcp_f32_e32 v112, v112
	v_rcp_f32_e32 v113, v113
	v_pk_mul_f32 v[2:3], v[2:3], v[130:131] op_sel_hi:[1,0]
	v_pk_mul_f32 v[4:5], v[4:5], v[130:131] op_sel_hi:[1,0]
	s_andn2_b64 vcc, exec, s[0:1]
	v_pk_mul_f32 v[110:111], v[110:111], v[112:113]
	s_nop 0
	v_pk_mul_f32 v[108:109], v[108:109], v[110:111]
	v_mul_f32_e32 v110, 0xbfb8aa3b, v102
	v_mul_f32_e32 v111, 0xbfb8aa3b, v103
	v_exp_f32_e32 v110, v110
	v_exp_f32_e32 v111, v111
	v_add_f32_e32 v110, 1.0, v110
	v_add_f32_e32 v111, 1.0, v111
	v_rcp_f32_e32 v110, v110
	v_rcp_f32_e32 v111, v111
	s_nop 0
	v_pk_mul_f32 v[102:103], v[102:103], v[110:111]
	s_nop 0
	v_pk_mul_f32 v[102:103], v[98:99], v[102:103]
	v_pk_mul_f32 v[98:99], v[104:105], v[192:193] op_sel_hi:[1,0]
	s_nop 0
	v_mul_f32_e32 v104, 0xbfb8aa3b, v98
	v_mul_f32_e32 v105, 0xbfb8aa3b, v99
	v_exp_f32_e32 v104, v104
	v_exp_f32_e32 v105, v105
	v_add_f32_e32 v104, 1.0, v104
	v_add_f32_e32 v105, 1.0, v105
	v_rcp_f32_e32 v104, v104
	v_rcp_f32_e32 v105, v105
	s_nop 0
	v_pk_mul_f32 v[98:99], v[98:99], v[104:105]
	s_nop 0
	v_pk_mul_f32 v[104:105], v[100:101], v[98:99]
	v_cvt_pk_bf16_f32 v100, v102, v103
	v_mad_i64_i32 v[102:103], s[4:5], v186, s9, v[114:115]
	v_cvt_pk_bf16_f32 v98, v106, v107
	v_cvt_pk_bf16_f32 v99, v108, v109
	v_cvt_pk_bf16_f32 v101, v104, v105
	v_lshl_add_u64 v[102:103], v[102:103], 0, v[116:117]
	global_store_dwordx4 v[102:103], v[98:101], off
	s_nop 1
	v_mul_f32_e32 v98, 0xbfb8aa3b, v94
	v_mul_f32_e32 v99, 0xbfb8aa3b, v95
	v_exp_f32_e32 v98, v98
	v_exp_f32_e32 v99, v99
	v_add_f32_e32 v98, 1.0, v98
	v_add_f32_e32 v99, 1.0, v99
	v_rcp_f32_e32 v98, v98
	v_rcp_f32_e32 v99, v99
	s_nop 0
	v_pk_mul_f32 v[94:95], v[94:95], v[98:99]
	s_nop 0
	v_pk_mul_f32 v[90:91], v[90:91], v[94:95]
	v_pk_mul_f32 v[94:95], v[96:97], v[148:149] op_sel_hi:[1,0]
	s_nop 0
	v_mul_f32_e32 v96, 0xbfb8aa3b, v94
	v_mul_f32_e32 v97, 0xbfb8aa3b, v95
	v_exp_f32_e32 v96, v96
	v_exp_f32_e32 v97, v97
	v_add_f32_e32 v96, 1.0, v96
	v_add_f32_e32 v97, 1.0, v97
	v_rcp_f32_e32 v96, v96
	v_rcp_f32_e32 v97, v97
	s_nop 0
	v_pk_mul_f32 v[94:95], v[94:95], v[96:97]
	s_nop 0
	v_pk_mul_f32 v[92:93], v[92:93], v[94:95]
	v_mul_f32_e32 v94, 0xbfb8aa3b, v86
	v_mul_f32_e32 v95, 0xbfb8aa3b, v87
	v_exp_f32_e32 v94, v94
	v_exp_f32_e32 v95, v95
	v_add_f32_e32 v94, 1.0, v94
	v_add_f32_e32 v95, 1.0, v95
	v_rcp_f32_e32 v94, v94
	v_rcp_f32_e32 v95, v95
	s_nop 0
	v_pk_mul_f32 v[86:87], v[86:87], v[94:95]
	s_nop 0
	v_pk_mul_f32 v[86:87], v[82:83], v[86:87]
	v_pk_mul_f32 v[82:83], v[88:89], v[148:149] op_sel_hi:[1,0]
	s_nop 0
	v_mul_f32_e32 v88, 0xbfb8aa3b, v82
	v_mul_f32_e32 v89, 0xbfb8aa3b, v83
	v_exp_f32_e32 v88, v88
	v_exp_f32_e32 v89, v89
	v_add_f32_e32 v88, 1.0, v88
	v_add_f32_e32 v89, 1.0, v89
	v_rcp_f32_e32 v88, v88
	v_rcp_f32_e32 v89, v89
	s_nop 0
	v_pk_mul_f32 v[82:83], v[82:83], v[88:89]
	s_nop 0
	v_pk_mul_f32 v[88:89], v[84:85], v[82:83]
	v_cvt_pk_bf16_f32 v84, v86, v87
	v_mad_i64_i32 v[86:87], s[4:5], v184, s9, v[114:115]
	v_cvt_pk_bf16_f32 v82, v90, v91
	v_cvt_pk_bf16_f32 v83, v92, v93
	v_cvt_pk_bf16_f32 v85, v88, v89
	v_lshl_add_u64 v[86:87], v[86:87], 0, v[116:117]
	global_store_dwordx4 v[86:87], v[82:85], off
	s_nop 1
	v_mul_f32_e32 v82, 0xbfb8aa3b, v78
	v_mul_f32_e32 v83, 0xbfb8aa3b, v79
	v_exp_f32_e32 v82, v82
	v_exp_f32_e32 v83, v83
	v_add_f32_e32 v82, 1.0, v82
	v_add_f32_e32 v83, 1.0, v83
	v_rcp_f32_e32 v82, v82
	v_rcp_f32_e32 v83, v83
	s_nop 0
	v_pk_mul_f32 v[78:79], v[78:79], v[82:83]
	s_nop 0
	v_pk_mul_f32 v[74:75], v[74:75], v[78:79]
	v_pk_mul_f32 v[78:79], v[80:81], v[146:147] op_sel_hi:[1,0]
	s_nop 0
	v_mul_f32_e32 v80, 0xbfb8aa3b, v78
	v_mul_f32_e32 v81, 0xbfb8aa3b, v79
	v_exp_f32_e32 v80, v80
	v_exp_f32_e32 v81, v81
	v_add_f32_e32 v80, 1.0, v80
	v_add_f32_e32 v81, 1.0, v81
	v_rcp_f32_e32 v80, v80
	v_rcp_f32_e32 v81, v81
	s_nop 0
	v_pk_mul_f32 v[78:79], v[78:79], v[80:81]
	s_nop 0
	v_pk_mul_f32 v[76:77], v[76:77], v[78:79]
	v_mul_f32_e32 v78, 0xbfb8aa3b, v70
	v_mul_f32_e32 v79, 0xbfb8aa3b, v71
	v_exp_f32_e32 v78, v78
	v_exp_f32_e32 v79, v79
	v_add_f32_e32 v78, 1.0, v78
	v_add_f32_e32 v79, 1.0, v79
	v_rcp_f32_e32 v78, v78
	v_rcp_f32_e32 v79, v79
	s_nop 0
	v_pk_mul_f32 v[70:71], v[70:71], v[78:79]
	s_nop 0
	v_pk_mul_f32 v[70:71], v[66:67], v[70:71]
	v_pk_mul_f32 v[66:67], v[72:73], v[146:147] op_sel_hi:[1,0]
	s_nop 0
	v_mul_f32_e32 v72, 0xbfb8aa3b, v66
	v_mul_f32_e32 v73, 0xbfb8aa3b, v67
	v_exp_f32_e32 v72, v72
	v_exp_f32_e32 v73, v73
	v_add_f32_e32 v72, 1.0, v72
	v_add_f32_e32 v73, 1.0, v73
	v_rcp_f32_e32 v72, v72
	v_rcp_f32_e32 v73, v73
	s_nop 0
	v_pk_mul_f32 v[66:67], v[66:67], v[72:73]
	s_nop 0
	v_pk_mul_f32 v[72:73], v[68:69], v[66:67]
	v_cvt_pk_bf16_f32 v68, v70, v71
	v_mad_i64_i32 v[70:71], s[4:5], v182, s9, v[114:115]
	v_cvt_pk_bf16_f32 v66, v74, v75
	v_cvt_pk_bf16_f32 v67, v76, v77
	v_cvt_pk_bf16_f32 v69, v72, v73
	v_lshl_add_u64 v[70:71], v[70:71], 0, v[116:117]
	global_store_dwordx4 v[70:71], v[66:69], off
	s_nop 1
	v_mul_f32_e32 v66, 0xbfb8aa3b, v62
	v_mul_f32_e32 v67, 0xbfb8aa3b, v63
	v_exp_f32_e32 v66, v66
	v_exp_f32_e32 v67, v67
	v_add_f32_e32 v66, 1.0, v66
	v_add_f32_e32 v67, 1.0, v67
	v_rcp_f32_e32 v66, v66
	v_rcp_f32_e32 v67, v67
	s_nop 0
	v_pk_mul_f32 v[62:63], v[62:63], v[66:67]
	s_nop 0
	v_pk_mul_f32 v[58:59], v[58:59], v[62:63]
	v_pk_mul_f32 v[62:63], v[64:65], v[140:141] op_sel_hi:[1,0]
	s_nop 0
	v_mul_f32_e32 v64, 0xbfb8aa3b, v62
	v_mul_f32_e32 v65, 0xbfb8aa3b, v63
	v_exp_f32_e32 v64, v64
	v_exp_f32_e32 v65, v65
	v_add_f32_e32 v64, 1.0, v64
	v_add_f32_e32 v65, 1.0, v65
	v_rcp_f32_e32 v64, v64
	v_rcp_f32_e32 v65, v65
	s_nop 0
	v_pk_mul_f32 v[62:63], v[62:63], v[64:65]
	s_nop 0
	v_pk_mul_f32 v[60:61], v[60:61], v[62:63]
	v_mul_f32_e32 v62, 0xbfb8aa3b, v54
	v_mul_f32_e32 v63, 0xbfb8aa3b, v55
	v_exp_f32_e32 v62, v62
	v_exp_f32_e32 v63, v63
	v_add_f32_e32 v62, 1.0, v62
	v_add_f32_e32 v63, 1.0, v63
	v_rcp_f32_e32 v62, v62
	v_rcp_f32_e32 v63, v63
	s_nop 0
	v_pk_mul_f32 v[54:55], v[54:55], v[62:63]
	s_nop 0
	v_pk_mul_f32 v[54:55], v[50:51], v[54:55]
	v_pk_mul_f32 v[50:51], v[56:57], v[140:141] op_sel_hi:[1,0]
	s_nop 0
	v_mul_f32_e32 v56, 0xbfb8aa3b, v50
	v_mul_f32_e32 v57, 0xbfb8aa3b, v51
	v_exp_f32_e32 v56, v56
	v_exp_f32_e32 v57, v57
	v_add_f32_e32 v56, 1.0, v56
	v_add_f32_e32 v57, 1.0, v57
	v_rcp_f32_e32 v56, v56
	v_rcp_f32_e32 v57, v57
	s_nop 0
	v_pk_mul_f32 v[50:51], v[50:51], v[56:57]
	s_nop 0
	v_pk_mul_f32 v[56:57], v[52:53], v[50:51]
	v_cvt_pk_bf16_f32 v52, v54, v55
	v_mad_i64_i32 v[54:55], s[4:5], v180, s9, v[114:115]
	v_cvt_pk_bf16_f32 v50, v58, v59
	v_cvt_pk_bf16_f32 v51, v60, v61
	v_cvt_pk_bf16_f32 v53, v56, v57
	v_lshl_add_u64 v[54:55], v[54:55], 0, v[116:117]
	global_store_dwordx4 v[54:55], v[50:53], off
	s_nop 1
	v_mul_f32_e32 v50, 0xbfb8aa3b, v46
	v_mul_f32_e32 v51, 0xbfb8aa3b, v47
	v_exp_f32_e32 v50, v50
	v_exp_f32_e32 v51, v51
	v_add_f32_e32 v50, 1.0, v50
	v_add_f32_e32 v51, 1.0, v51
	v_rcp_f32_e32 v50, v50
	v_rcp_f32_e32 v51, v51
	s_nop 0
	v_pk_mul_f32 v[46:47], v[46:47], v[50:51]
	s_nop 0
	v_pk_mul_f32 v[42:43], v[42:43], v[46:47]
	v_pk_mul_f32 v[46:47], v[48:49], v[138:139] op_sel_hi:[1,0]
	s_nop 0
	v_mul_f32_e32 v48, 0xbfb8aa3b, v46
	v_mul_f32_e32 v49, 0xbfb8aa3b, v47
	v_exp_f32_e32 v48, v48
	v_exp_f32_e32 v49, v49
	v_add_f32_e32 v48, 1.0, v48
	v_add_f32_e32 v49, 1.0, v49
	v_rcp_f32_e32 v48, v48
	v_rcp_f32_e32 v49, v49
	s_nop 0
	v_pk_mul_f32 v[46:47], v[46:47], v[48:49]
	s_nop 0
	v_pk_mul_f32 v[44:45], v[44:45], v[46:47]
	v_mul_f32_e32 v46, 0xbfb8aa3b, v38
	v_mul_f32_e32 v47, 0xbfb8aa3b, v39
	v_exp_f32_e32 v46, v46
	v_exp_f32_e32 v47, v47
	v_add_f32_e32 v46, 1.0, v46
	v_add_f32_e32 v47, 1.0, v47
	v_rcp_f32_e32 v46, v46
	v_rcp_f32_e32 v47, v47
	s_nop 0
	v_pk_mul_f32 v[38:39], v[38:39], v[46:47]
	s_nop 0
	v_pk_mul_f32 v[38:39], v[34:35], v[38:39]
	v_pk_mul_f32 v[34:35], v[40:41], v[138:139] op_sel_hi:[1,0]
	s_nop 0
	v_mul_f32_e32 v40, 0xbfb8aa3b, v34
	v_mul_f32_e32 v41, 0xbfb8aa3b, v35
	v_exp_f32_e32 v40, v40
	v_exp_f32_e32 v41, v41
	v_add_f32_e32 v40, 1.0, v40
	v_add_f32_e32 v41, 1.0, v41
	v_rcp_f32_e32 v40, v40
	v_rcp_f32_e32 v41, v41
	s_nop 0
	v_pk_mul_f32 v[34:35], v[34:35], v[40:41]
	s_nop 0
	v_pk_mul_f32 v[40:41], v[36:37], v[34:35]
	v_cvt_pk_bf16_f32 v36, v38, v39
	v_mad_i64_i32 v[38:39], s[4:5], v178, s9, v[114:115]
	v_cvt_pk_bf16_f32 v34, v42, v43
	v_cvt_pk_bf16_f32 v35, v44, v45
	v_cvt_pk_bf16_f32 v37, v40, v41
	v_lshl_add_u64 v[38:39], v[38:39], 0, v[116:117]
	global_store_dwordx4 v[38:39], v[34:37], off
	s_nop 1
	v_mul_f32_e32 v34, 0xbfb8aa3b, v30
	v_mul_f32_e32 v35, 0xbfb8aa3b, v31
	v_exp_f32_e32 v34, v34
	v_exp_f32_e32 v35, v35
	v_add_f32_e32 v34, 1.0, v34
	v_add_f32_e32 v35, 1.0, v35
	v_rcp_f32_e32 v34, v34
	v_rcp_f32_e32 v35, v35
	s_nop 0
	v_pk_mul_f32 v[30:31], v[30:31], v[34:35]
	s_nop 0
	v_pk_mul_f32 v[26:27], v[26:27], v[30:31]
	v_pk_mul_f32 v[30:31], v[32:33], v[132:133] op_sel_hi:[1,0]
	s_nop 0
	v_mul_f32_e32 v32, 0xbfb8aa3b, v30
	v_mul_f32_e32 v33, 0xbfb8aa3b, v31
	v_exp_f32_e32 v32, v32
	v_exp_f32_e32 v33, v33
	v_add_f32_e32 v32, 1.0, v32
	v_add_f32_e32 v33, 1.0, v33
	v_rcp_f32_e32 v32, v32
	v_rcp_f32_e32 v33, v33
	s_nop 0
	v_pk_mul_f32 v[30:31], v[30:31], v[32:33]
	s_nop 0
	v_pk_mul_f32 v[28:29], v[28:29], v[30:31]
	v_mul_f32_e32 v30, 0xbfb8aa3b, v22
	v_mul_f32_e32 v31, 0xbfb8aa3b, v23
	v_exp_f32_e32 v30, v30
	v_exp_f32_e32 v31, v31
	v_add_f32_e32 v30, 1.0, v30
	v_add_f32_e32 v31, 1.0, v31
	v_rcp_f32_e32 v30, v30
	v_rcp_f32_e32 v31, v31
	s_nop 0
	v_pk_mul_f32 v[22:23], v[22:23], v[30:31]
	s_nop 0
	v_pk_mul_f32 v[22:23], v[18:19], v[22:23]
	v_pk_mul_f32 v[18:19], v[24:25], v[132:133] op_sel_hi:[1,0]
	s_nop 0
	v_mul_f32_e32 v24, 0xbfb8aa3b, v18
	v_mul_f32_e32 v25, 0xbfb8aa3b, v19
	v_exp_f32_e32 v24, v24
	v_exp_f32_e32 v25, v25
	v_add_f32_e32 v24, 1.0, v24
	v_add_f32_e32 v25, 1.0, v25
	v_rcp_f32_e32 v24, v24
	v_rcp_f32_e32 v25, v25
	s_nop 0
	v_pk_mul_f32 v[18:19], v[18:19], v[24:25]
	s_nop 0
	v_pk_mul_f32 v[24:25], v[20:21], v[18:19]
	v_cvt_pk_bf16_f32 v20, v22, v23
	v_mad_i64_i32 v[22:23], s[4:5], v176, s9, v[114:115]
	v_cvt_pk_bf16_f32 v18, v26, v27
	v_cvt_pk_bf16_f32 v19, v28, v29
	v_cvt_pk_bf16_f32 v21, v24, v25
	v_lshl_add_u64 v[22:23], v[22:23], 0, v[116:117]
	global_store_dwordx4 v[22:23], v[18:21], off
	s_nop 1
	v_mul_f32_e32 v18, 0xbfb8aa3b, v14
	v_mul_f32_e32 v19, 0xbfb8aa3b, v15
	v_exp_f32_e32 v18, v18
	v_exp_f32_e32 v19, v19
	v_add_f32_e32 v18, 1.0, v18
	v_add_f32_e32 v19, 1.0, v19
	v_rcp_f32_e32 v18, v18
	v_rcp_f32_e32 v19, v19
	s_nop 0
	v_pk_mul_f32 v[14:15], v[14:15], v[18:19]
	s_nop 0
	v_pk_mul_f32 v[10:11], v[10:11], v[14:15]
	v_pk_mul_f32 v[14:15], v[16:17], v[130:131] op_sel_hi:[1,0]
	s_nop 0
	v_mul_f32_e32 v16, 0xbfb8aa3b, v14
	v_mul_f32_e32 v17, 0xbfb8aa3b, v15
	v_exp_f32_e32 v16, v16
	v_exp_f32_e32 v17, v17
	v_add_f32_e32 v16, 1.0, v16
	v_add_f32_e32 v17, 1.0, v17
	v_rcp_f32_e32 v16, v16
	v_rcp_f32_e32 v17, v17
	s_nop 0
	v_pk_mul_f32 v[14:15], v[14:15], v[16:17]
	s_nop 0
	v_pk_mul_f32 v[12:13], v[12:13], v[14:15]
	v_mul_f32_e32 v14, 0xbfb8aa3b, v6
	v_mul_f32_e32 v15, 0xbfb8aa3b, v7
	v_exp_f32_e32 v14, v14
	v_exp_f32_e32 v15, v15
	v_add_f32_e32 v14, 1.0, v14
	v_add_f32_e32 v15, 1.0, v15
	v_rcp_f32_e32 v14, v14
	v_rcp_f32_e32 v15, v15
	s_nop 0
	v_pk_mul_f32 v[6:7], v[6:7], v[14:15]
	s_nop 0
	v_pk_mul_f32 v[6:7], v[2:3], v[6:7]
	v_pk_mul_f32 v[2:3], v[8:9], v[130:131] op_sel_hi:[1,0]
	s_nop 0
	v_mul_f32_e32 v8, 0xbfb8aa3b, v2
	v_mul_f32_e32 v9, 0xbfb8aa3b, v3
	v_exp_f32_e32 v8, v8
	v_exp_f32_e32 v9, v9
	v_add_f32_e32 v8, 1.0, v8
	v_add_f32_e32 v9, 1.0, v9
	v_rcp_f32_e32 v8, v8
	v_rcp_f32_e32 v9, v9
	s_nop 0
	v_pk_mul_f32 v[2:3], v[2:3], v[8:9]
	s_nop 0
	v_pk_mul_f32 v[8:9], v[4:5], v[2:3]
	v_cvt_pk_bf16_f32 v4, v6, v7
	v_mad_i64_i32 v[6:7], s[4:5], v174, s9, v[114:115]
	v_cvt_pk_bf16_f32 v2, v10, v11
	v_cvt_pk_bf16_f32 v3, v12, v13
	v_cvt_pk_bf16_f32 v5, v8, v9
	v_lshl_add_u64 v[6:7], v[6:7], 0, v[116:117]
	s_mov_b64 s[4:5], -1
	global_store_dwordx4 v[6:7], v[2:5], off
	s_cbranch_vccnz .LBB0_1438
	s_branch .LBB0_1437
